# v22 + attention mixer-A unit prologue: first K/V tile loaded before the Q fragments (Q waited at first use) + down-proj epilogue residual loads issued earlier
# speedup vs baseline: 1.0038x; 1.0038x over previous
; #define LAS __attribute__((address_space(3)))
; template <bool MASKED>
; __device__ __forceinline__ void tile64(const LAS unsigned char* buf, const bf16x8 (&qf)[4], f32x16& o0, f32x16& o1, float& l, int lane, int r32, int hi, const f32x16& cinit,
;                                        int a0, int b0, int a1, int b1) {
;     ...
;     const LAS unsigned char* kp = buf + r32 * KSTR + hi * 16;
;     const LAS unsigned char* vp = buf + K_BYTES + (4 * hi + ((lane & 15) >> 2)) * 64 + 32 * ((lane >> 4) & 1) + 8 * (lane & 3);
;     const int dq = 4 * hi - r32; const float NEG = -INFINITY;
;     bf16x8 kf0[4], kf1[4];
; #pragma unroll
;     for (int d0 = 0; d0 < 4; ++d0) { kf0[d0] = *(const LAS bf16x8*)(kp + d0 * 32); kf1[d0] = *(const LAS bf16x8*)(kp + 32 * KSTR + d0 * 32); }
;     T64_SB();
;     f32x16 s0 = cinit, s1 = cinit;
; #pragma unroll
;     for (int d0 = 0; d0 < 4; ++d0) s0 = __builtin_amdgcn_mfma_f32_32x32x16_bf16(kf0[d0], qf[d0], s0, 0, 0, 0);
;     s16x4 va[2][8];
; #pragma unroll
;     for (int dh = 0; dh < 2; ++dh)
; #pragma unroll
;         for (int j = 0; j < 8; ++j) va[dh][j] = vtr(vp + dh * V_HALF + j * 512);
;     T64_SB();
; #pragma unroll
;     for (int d0 = 0; d0 < 4; ++d0) {
;         s1 = __builtin_amdgcn_mfma_f32_32x32x16_bf16(kf1[d0], qf[d0], s1, 0, 0, 0);
; #pragma unroll
; template <int MODE, bool FIX> ...
;     ...
;         int nmask, nl1, tlu0;
;         if (MODE == 0) { const int tl1 = tl0 + NTL - 1; nmask = (tl0 == 0 ? 1 : 0) + (tl1 == 4 ? 1 : 0); tlu0 = tl0 > 1 ? tl0 : 1; nl1 = (tl1 < 3 ? tl1 : 3) - tlu0 + 1; }
;         else { nmask = NTL; nl1 = 0; tlu0 = 0; }
;         const int lbase = (MODE == 0) ? (b * SEQ + 64 * (rem >> 1) - 128) : lrow0;
;     ...
;         u32x4 kA, vA;
;         { const size_t ro_ = (size_t)ATT_SEQ_ROW(0) * INC; kA = *(const u32x4*)(gk + ro_); vA = *(const u32x4*)(gv + ro_); }
;         int i = 0;
;         for (; i < nmask; ++i) {
;             ATT_STEP_PRE(i)
;             if (MODE == 0) {
;                 const int tl = ATT_SEQ_TL(i); const int dA = 2 * tl - s_sub, dB = dA + 1;
;                 const int a0 = (dA < 0 || dA > 8) ? 99 : (dA == 0 ? 0 : -99), b0 = (dA < 0 || dA > 8) ? -99 : (dA == 8 ? 0 : 99);
;                 const int a1 = (dB < 0 || dB > 8) ? 99 : (dB == 0 ? 0 : -99), b1 = (dB < 0 || dB > 8) ? -99 : (dB == 8 ? 0 : 99);
;                 tile64<true>(buf, qf, o0, o1, l, lane, r32, hi, cinit, a0, b0, a1, b1);
.LBB0_655:
	s_and_b64 vcc, exec, s[70:71]
	s_cbranch_vccz .LBB0_572
	v_readlane_b32 s2, v255, 5
	v_readlane_b32 s3, v255, 6
	s_lshl_b32 s0, s93, 2
	v_mov_b32_e32 v243, s0
	s_nop 4
	global_load_dword v243, v243, s[2:3]
	s_lshl_b32 s78, s75, 12
	v_or_b32_e32 v128, s78, v225
	s_or_b32 s77, s83, s78
	s_lshl_b32 s1, s75, 8
	s_sub_i32 s53, 0x41, s72
	s_add_i32 s0, s77, 0xffffff80
	s_lshl_b32 s86, s81, 1
	s_add_i32 s1, s1, 0x8000
	s_lshl_b32 s2, s97, 7
	s_mov_b32 s3, s87
	s_cmp_lt_u32 s72, 62
	v_lshl_add_u64 v[130:131], v[180:181], 0, s[2:3]
	s_cselect_b64 s[2:3], -1, 0
	s_cmp_gt_u32 s72, 1
	s_cselect_b64 s[88:89], -1, 0
	v_cndmask_b32_e64 v0, 0, 1, s[2:3]
	s_and_b64 s[2:3], s[88:89], exec
	s_cselect_b32 s52, 0, 0x100
	v_readfirstlane_b32 s2, v0
	s_cmp_lg_u64 s[88:89], 0
	s_addc_u32 s2, s2, 0
	s_max_i32 s72, s90, 1
	s_min_u32 s3, s53, 3
	s_sub_i32 s3, s3, s72
	s_lshl_b32 s70, s72, 6
	s_cmp_eq_u32 s2, 0
	s_cselect_b32 s52, s70, s52
	s_add_i32 s52, s52, s0
	v_mad_i64_i32 v[2:3], s[70:71], s52, v221, v[130:131]
	v_readlane_b32 s4, v255, 20
	v_readlane_b32 s5, v255, 21
	s_mov_b32 s36, 1
	global_load_dwordx4 v[108:111], v[2:3], off offset:1024
	global_load_dwordx4 v[112:115], v[2:3], off offset:1280
	s_nop 1
	v_mov_b64_e32 v[2:3], s[4:5]
	v_mad_i64_i32 v[2:3], s[4:5], v128, v221, v[2:3]
	s_nop 1
	v_lshl_add_u64 v[2:3], v[2:3], 0, s[86:87]
	v_lshl_add_u64 v[2:3], v[176:177], 1, v[2:3]
	global_load_dwordx4 v[92:95], v[2:3], off
	global_load_dwordx4 v[96:99], v[2:3], off offset:32
	global_load_dwordx4 v[100:103], v[2:3], off offset:64
	global_load_dwordx4 v[104:107], v[2:3], off offset:96
	s_cmp_lg_u32 s2, 0
	s_mov_b64 s[70:71], -1
	s_cbranch_scc0 .LBB0_660
	s_max_i32 s52, s80, 1
	s_add_i32 s52, s52, s91
	s_lshl_b32 s70, s52, 6
	s_add_i32 s78, s78, s70
	s_lshl_b32 s70, s2, 6
	s_sub_i32 s70, s78, s70
	v_mov_b32_e32 v150, 0
	s_waitcnt vmcnt(5)
	v_mov_b64_e32 v[2:3], v[108:109]
	s_waitcnt vmcnt(4)
	v_mov_b64_e32 v[6:7], v[112:113]
	s_sub_i32 s52, s72, s2
	s_add_i32 s75, s77, 0x80
	s_add_i32 s77, s2, s3
	s_sub_i32 s78, s70, 64
	s_mov_b32 s79, 0
	v_mov_b64_e32 v[4:5], v[110:111]
	v_mov_b64_e32 v[8:9], v[114:115]
	s_mov_b32 s70, 0
	v_mov_b32_e32 v32, 0
	v_mov_b32_e32 v33, v150
	v_mov_b32_e32 v34, v150
	v_mov_b32_e32 v35, v150
	v_mov_b32_e32 v36, v150
	v_mov_b32_e32 v37, v150
	v_mov_b32_e32 v38, v150
	v_mov_b32_e32 v39, v150
	v_mov_b32_e32 v40, v150
	v_mov_b32_e32 v41, v150
	v_mov_b32_e32 v42, v150
	v_mov_b32_e32 v43, v150
	v_mov_b32_e32 v44, v150
	v_mov_b32_e32 v45, v150
	v_mov_b32_e32 v46, v150
	v_mov_b32_e32 v47, v150
	v_mov_b32_e32 v48, 0
	v_mov_b32_e32 v49, v150
	v_mov_b32_e32 v50, v150
	v_mov_b32_e32 v51, v150
	v_mov_b32_e32 v52, v150
	v_mov_b32_e32 v53, v150
	v_mov_b32_e32 v54, v150
	v_mov_b32_e32 v55, v150
	v_mov_b32_e32 v56, v150
	v_mov_b32_e32 v57, v150
	v_mov_b32_e32 v58, v150
	v_mov_b32_e32 v59, v150
	v_mov_b32_e32 v60, v150
	v_mov_b32_e32 v61, v150
	v_mov_b32_e32 v62, v150
	v_mov_b32_e32 v63, v150
.LBB0_658:
	s_add_i32 s80, s70, 1
	s_cmp_lt_u32 s70, s77
	v_add_u32_e32 v0, s79, v220
	s_cselect_b32 s70, s78, s1
	v_add_u32_e32 v10, s79, v218
	s_cmp_lg_u32 s36, 0
	s_cbranch_scc1 .La_nw1
	s_waitcnt vmcnt(0)
.La_nw1:
	s_mov_b32 s36, 0
	ds_write_b128 v0, v[2:5]
	ds_write_b128 v10, v[6:9]
	s_cmp_lt_u32 s80, s2
	s_cselect_b32 s70, s75, s70
	s_waitcnt lgkmcnt(0)
	s_barrier
	v_mad_i64_i32 v[6:7], s[70:71], s70, v221, v[130:131]
	global_load_dwordx4 v[2:5], v[6:7], off offset:1024
	s_nop 0
	global_load_dwordx4 v[6:9], v[6:7], off offset:1280
	v_add_u32_e32 v0, s79, v219
	s_cmp_eq_u32 s79, 0
	s_cselect_b64 s[70:71], -1, 0
	s_and_b64 s[70:71], s[88:89], s[70:71]
	s_and_b64 s[70:71], s[70:71], exec
	s_cselect_b32 s81, 0, 8
	s_sub_i32 s82, s81, s74
	v_add_u32_e32 v244, s79, v217
	s_cmp_eq_u32 s82, 0
	s_cbranch_scc1 .Lam_v1
	s_cmp_eq_u32 s82, 7
	s_cbranch_scc1 .Lam_v4
	s_cmp_eq_u32 s82, 8
	s_cbranch_scc1 .Lam_v3
	ds_read_b128 v[108:111], v0 offset:4608
	ds_read_b128 v[112:115], v0 offset:4640
	ds_read_b128 v[116:119], v0 offset:4672
	ds_read_b128 v[120:123], v0 offset:4704
	ds_read_b64_tr_b16 v[132:133], v244 offset:11264
	ds_read_b64_tr_b16 v[134:135], v244 offset:11776
	ds_read_b64_tr_b16 v[136:137], v244 offset:12288
	ds_read_b64_tr_b16 v[138:139], v244 offset:12800
	ds_read_b64_tr_b16 v[152:153], v244 offset:15424
	ds_read_b64_tr_b16 v[154:155], v244 offset:15936
	ds_read_b64_tr_b16 v[156:157], v244 offset:16448
	ds_read_b64_tr_b16 v[158:159], v244 offset:16960
	s_waitcnt lgkmcnt(8)
	s_waitcnt vmcnt(2)
	v_mfma_f32_32x32x16_bf16 v[64:79], v[108:111], v[92:95], v[226:241]
	v_mfma_f32_32x32x16_bf16 v[64:79], v[112:115], v[96:99], v[64:79]
	v_mfma_f32_32x32x16_bf16 v[64:79], v[116:119], v[100:103], v[64:79]
	v_mfma_f32_32x32x16_bf16 v[64:79], v[120:123], v[104:107], v[64:79]
	s_nop 11
	v_exp_f32_e32 v15, v64
	v_exp_f32_e32 v149, v65
	v_exp_f32_e32 v161, v66
	v_exp_f32_e32 v163, v67
	v_exp_f32_e32 v109, v68
	v_exp_f32_e32 v111, v69
	v_exp_f32_e32 v165, v70
	v_exp_f32_e32 v167, v71
	v_exp_f32_e32 v113, v72
	v_exp_f32_e32 v115, v73
	v_exp_f32_e32 v169, v74
	v_exp_f32_e32 v171, v75
	v_exp_f32_e32 v89, v76
	v_exp_f32_e32 v117, v77
	v_exp_f32_e32 v91, v78
	v_exp_f32_e32 v119, v79
	v_cvt_pk_bf16_f32 v10, v15, v149
	v_cvt_pk_bf16_f32 v11, v161, v163
	v_cvt_pk_bf16_f32 v12, v109, v111
	v_cvt_pk_bf16_f32 v13, v165, v167
	v_cvt_pk_bf16_f32 v64, v113, v115
	v_cvt_pk_bf16_f32 v65, v169, v171
	v_cvt_pk_bf16_f32 v66, v89, v117
	v_cvt_pk_bf16_f32 v67, v91, v119
	s_nop 1
	s_waitcnt lgkmcnt(0)
	v_mfma_f32_32x32x16_bf16 v[32:47], v[132:135], v[10:13], v[32:47]
	v_mfma_f32_32x32x16_bf16 v[48:63], v[152:155], v[10:13], v[48:63]
	v_mfma_f32_32x32x16_bf16 v[32:47], v[136:139], v[64:67], v[32:47]
	v_mfma_f32_32x32x16_bf16 v[48:63], v[156:159], v[64:67], v[48:63]
	v_add_f32_e32 v15, v15, v149
	v_add_f32_e32 v161, v161, v163
	v_add_f32_e32 v109, v109, v111
	v_add_f32_e32 v165, v165, v167
	v_add_f32_e32 v113, v113, v115
	v_add_f32_e32 v169, v169, v171
	v_add_f32_e32 v89, v89, v117
	v_add_f32_e32 v91, v91, v119
	v_add_f32_e32 v15, v15, v161
	v_add_f32_e32 v109, v109, v165
	v_add_f32_e32 v113, v113, v169
	v_add_f32_e32 v89, v89, v91
	v_add_f32_e32 v15, v15, v109
	v_add_f32_e32 v113, v113, v89
	v_add_f32_e32 v15, v15, v113
	v_add_f32_e32 v150, v150, v15
	s_branch .Lam_tail
; template <bool MASKED>
; __device__ __forceinline__ void tile64(const LAS unsigned char* buf, const bf16x8 (&qf)[4], f32x16& o0, f32x16& o1, float& l, int lane, int r32, int hi, const f32x16& cinit,
;                                        int a0, int b0, int a1, int b1) {
;     ...
;     const LAS unsigned char* kp = buf + r32 * KSTR + hi * 16;
;     const LAS unsigned char* vp = buf + K_BYTES + (4 * hi + ((lane & 15) >> 2)) * 64 + 32 * ((lane >> 4) & 1) + 8 * (lane & 3);
;     const int dq = 4 * hi - r32; const float NEG = -INFINITY;
;     bf16x8 kf0[4], kf1[4];
; #pragma unroll
;     for (int d0 = 0; d0 < 4; ++d0) { kf0[d0] = *(const LAS bf16x8*)(kp + d0 * 32); kf1[d0] = *(const LAS bf16x8*)(kp + 32 * KSTR + d0 * 32); }
;     T64_SB();
;     f32x16 s0 = cinit, s1 = cinit;
; #pragma unroll
;     for (int d0 = 0; d0 < 4; ++d0) s0 = __builtin_amdgcn_mfma_f32_32x32x16_bf16(kf0[d0], qf[d0], s0, 0, 0, 0);
;     s16x4 va[2][8];
; #pragma unroll
;     for (int dh = 0; dh < 2; ++dh)
; #pragma unroll
;         for (int j = 0; j < 8; ++j) va[dh][j] = vtr(vp + dh * V_HALF + j * 512);
;     T64_SB();
; #pragma unroll
;     for (int d0 = 0; d0 < 4; ++d0) {
;         s1 = __builtin_amdgcn_mfma_f32_32x32x16_bf16(kf1[d0], qf[d0], s1, 0, 0, 0);
; #pragma unroll
;         for (int r = 4 * d0; r < 4 * d0 + 4; ++r) { if (MASKED) { const int t = (r & 3) + 8 * (r >> 2) + dq; if (t < a0 || t > b0) s0[r] = NEG; } s0[r] = __builtin_amdgcn_exp2f(s0[r]); }
;         T64_SB();
;     }
;     u32x4 w00, w01;
;     w00.x = cvtpk(s0[0], s0[1]); w00.y = cvtpk(s0[2], s0[3]); w00.z = cvtpk(s0[4], s0[5]); w00.w = cvtpk(s0[6], s0[7]);
;     w01.x = cvtpk(s0[8], s0[9]); w01.y = cvtpk(s0[10], s0[11]); w01.z = cvtpk(s0[12], s0[13]); w01.w = cvtpk(s0[14], s0[15]);
;     const bf16x8 p00 = __builtin_bit_cast(bf16x8, w00), p01 = __builtin_bit_cast(bf16x8, w01);
;     l += (((s0[0] + s0[1]) + (s0[2] + s0[3])) + ((s0[4] + s0[5]) + (s0[6] + s0[7]))) + (((s0[8] + s0[9]) + (s0[10] + s0[11])) + ((s0[12] + s0[13]) + (s0[14] + s0[15])));
;     ...
;     T64_SB();
;     o0 = __builtin_amdgcn_mfma_f32_32x32x16_bf16(T64_VF(0, 0), p00, o0, 0, 0, 0); T64_EXP1(0);  T64_SB();
;     o1 = __builtin_amdgcn_mfma_f32_32x32x16_bf16(T64_VF(1, 0), p00, o1, 0, 0, 0); T64_EXP1(4);  T64_SB();
;     o0 = __builtin_amdgcn_mfma_f32_32x32x16_bf16(T64_VF(0, 1), p01, o0, 0, 0, 0); T64_EXP1(8);  T64_SB();
.Lam_v1:
	ds_read_b128 v[10:13], v0
	ds_read_b128 v[64:67], v0 offset:32
	ds_read_b128 v[108:111], v0 offset:4608
	ds_read_b128 v[112:115], v0 offset:4640
	ds_read_b128 v[68:71], v0 offset:64
	ds_read_b128 v[72:75], v0 offset:96
	ds_read_b128 v[116:119], v0 offset:4672
	ds_read_b128 v[120:123], v0 offset:4704
	s_waitcnt lgkmcnt(7)
	s_waitcnt vmcnt(2)
	v_mfma_f32_32x32x16_bf16 v[76:91], v[10:13], v[92:95], v[226:241]
	ds_read_b64_tr_b16 v[10:11], v244 offset:9216
	ds_read_b64_tr_b16 v[12:13], v244 offset:9728
	ds_read_b64_tr_b16 v[124:125], v244 offset:10240
	ds_read_b64_tr_b16 v[126:127], v244 offset:10752
	ds_read_b64_tr_b16 v[132:133], v244 offset:11264
	ds_read_b64_tr_b16 v[134:135], v244 offset:11776
	ds_read_b64_tr_b16 v[136:137], v244 offset:12288
	ds_read_b64_tr_b16 v[138:139], v244 offset:12800
	ds_read_b64_tr_b16 v[140:141], v244 offset:13376
	ds_read_b64_tr_b16 v[142:143], v244 offset:13888
	ds_read_b64_tr_b16 v[144:145], v244 offset:14400
	ds_read_b64_tr_b16 v[146:147], v244 offset:14912
	ds_read_b64_tr_b16 v[152:153], v244 offset:15424
	ds_read_b64_tr_b16 v[154:155], v244 offset:15936
	ds_read_b64_tr_b16 v[156:157], v244 offset:16448
	ds_read_b64_tr_b16 v[158:159], v244 offset:16960
	s_waitcnt lgkmcnt(14)
	v_mfma_f32_32x32x16_bf16 v[76:91], v[64:67], v[96:99], v[76:91]
	v_mfma_f32_32x32x16_bf16 v[76:91], v[68:71], v[100:103], v[76:91]
	v_mfma_f32_32x32x16_bf16 v[76:91], v[72:75], v[104:107], v[76:91]
	s_nop 11
	v_exp_f32_e32 v14, v76
	v_exp_f32_e32 v148, v77
	v_exp_f32_e32 v160, v78
	v_exp_f32_e32 v162, v79
	s_waitcnt vmcnt(2)
	v_mfma_f32_32x32x16_bf16 v[64:79], v[108:111], v[92:95], v[16:31]
	v_exp_f32_e32 v108, v80
	v_exp_f32_e32 v110, v81
	v_exp_f32_e32 v164, v82
	v_exp_f32_e32 v166, v83
	v_mfma_f32_32x32x16_bf16 v[64:79], v[112:115], v[96:99], v[64:79]
	v_exp_f32_e32 v112, v84
	v_exp_f32_e32 v114, v85
	v_exp_f32_e32 v168, v86
	v_exp_f32_e32 v170, v87
	v_mfma_f32_32x32x16_bf16 v[64:79], v[116:119], v[100:103], v[64:79]
	v_exp_f32_e32 v88, v88
	v_exp_f32_e32 v116, v89
	v_exp_f32_e32 v90, v90
	v_exp_f32_e32 v118, v91
	v_mfma_f32_32x32x16_bf16 v[64:79], v[120:123], v[104:107], v[64:79]
	v_cvt_pk_bf16_f32 v80, v14, v148
	v_cvt_pk_bf16_f32 v81, v160, v162
	v_cvt_pk_bf16_f32 v82, v108, v110
	v_cvt_pk_bf16_f32 v83, v164, v166
	v_cvt_pk_bf16_f32 v84, v112, v114
	v_cvt_pk_bf16_f32 v85, v168, v170
	v_cvt_pk_bf16_f32 v86, v88, v116
	v_cvt_pk_bf16_f32 v87, v90, v118
	s_nop 1
	v_mfma_f32_32x32x16_bf16 v[32:47], v[10:13], v[80:83], v[32:47]
	s_nop 2
	v_exp_f32_e32 v15, v64
	v_exp_f32_e32 v149, v65
	v_exp_f32_e32 v161, v66
	v_exp_f32_e32 v163, v67
	s_waitcnt lgkmcnt(6)
	v_mfma_f32_32x32x16_bf16 v[48:63], v[140:143], v[80:83], v[48:63]
	v_exp_f32_e32 v109, v68
	v_exp_f32_e32 v111, v69
	v_exp_f32_e32 v165, v70
	v_exp_f32_e32 v167, v71
	v_mfma_f32_32x32x16_bf16 v[32:47], v[124:127], v[84:87], v[32:47]
	v_exp_f32_e32 v113, v72
	v_exp_f32_e32 v115, v73
	v_exp_f32_e32 v169, v74
	v_exp_f32_e32 v171, v75
	s_waitcnt lgkmcnt(4)
	v_mfma_f32_32x32x16_bf16 v[48:63], v[144:147], v[84:87], v[48:63]
	v_exp_f32_e32 v89, v76
	v_exp_f32_e32 v117, v77
	v_exp_f32_e32 v91, v78
	v_exp_f32_e32 v119, v79
	v_cvt_pk_bf16_f32 v10, v15, v149
	v_cvt_pk_bf16_f32 v11, v161, v163
	v_cvt_pk_bf16_f32 v12, v109, v111
	v_cvt_pk_bf16_f32 v13, v165, v167
	v_pk_add_f32 v[14:15], v[14:15], v[148:149]
	v_pk_add_f32 v[160:161], v[160:161], v[162:163]
	v_mfma_f32_32x32x16_bf16 v[32:47], v[132:135], v[10:13], v[32:47]
	v_cvt_pk_bf16_f32 v64, v113, v115
	v_cvt_pk_bf16_f32 v65, v169, v171
	v_cvt_pk_bf16_f32 v66, v89, v117
	v_cvt_pk_bf16_f32 v67, v91, v119
	v_pk_add_f32 v[108:109], v[108:109], v[110:111]
	v_pk_add_f32 v[164:165], v[164:165], v[166:167]
	s_waitcnt lgkmcnt(2)
	v_mfma_f32_32x32x16_bf16 v[48:63], v[152:155], v[10:13], v[48:63]
	v_pk_add_f32 v[112:113], v[112:113], v[114:115]
	v_pk_add_f32 v[168:169], v[168:169], v[170:171]
	v_pk_add_f32 v[88:89], v[88:89], v[116:117]
	v_pk_add_f32 v[90:91], v[90:91], v[118:119]
	v_pk_add_f32 v[14:15], v[14:15], v[160:161]
	v_pk_add_f32 v[108:109], v[108:109], v[164:165]
	v_mfma_f32_32x32x16_bf16 v[32:47], v[136:139], v[64:67], v[32:47]
	v_pk_add_f32 v[112:113], v[112:113], v[168:169]
	v_pk_add_f32 v[88:89], v[88:89], v[90:91]
	v_pk_add_f32 v[14:15], v[14:15], v[108:109]
	v_pk_add_f32 v[112:113], v[112:113], v[88:89]
	s_waitcnt lgkmcnt(0)
	v_mfma_f32_32x32x16_bf16 v[48:63], v[156:159], v[64:67], v[48:63]
	v_pk_add_f32 v[14:15], v[14:15], v[112:113]
	s_nop 0
	v_add_f32_e32 v0, v150, v14
	v_add_f32_e32 v150, v0, v15
	s_branch .Lam_tail
; template <bool MASKED>
; __device__ __forceinline__ void tile64(const LAS unsigned char* buf, const bf16x8 (&qf)[4], f32x16& o0, f32x16& o1, float& l, int lane, int r32, int hi, const f32x16& cinit,
;                                        int a0, int b0, int a1, int b1) {
;     ...
;     const LAS unsigned char* kp = buf + r32 * KSTR + hi * 16;
;     const LAS unsigned char* vp = buf + K_BYTES + (4 * hi + ((lane & 15) >> 2)) * 64 + 32 * ((lane >> 4) & 1) + 8 * (lane & 3);
;     const int dq = 4 * hi - r32; const float NEG = -INFINITY;
;     bf16x8 kf0[4], kf1[4];
; #pragma unroll
;     for (int d0 = 0; d0 < 4; ++d0) { kf0[d0] = *(const LAS bf16x8*)(kp + d0 * 32); kf1[d0] = *(const LAS bf16x8*)(kp + 32 * KSTR + d0 * 32); }
;     T64_SB();
;     f32x16 s0 = cinit, s1 = cinit;
; #pragma unroll
;     for (int d0 = 0; d0 < 4; ++d0) s0 = __builtin_amdgcn_mfma_f32_32x32x16_bf16(kf0[d0], qf[d0], s0, 0, 0, 0);
;     s16x4 va[2][8];
; #pragma unroll
;     for (int dh = 0; dh < 2; ++dh)
; #pragma unroll
;         for (int j = 0; j < 8; ++j) va[dh][j] = vtr(vp + dh * V_HALF + j * 512);
;     T64_SB();
; #pragma unroll
;     for (int d0 = 0; d0 < 4; ++d0) {
;         s1 = __builtin_amdgcn_mfma_f32_32x32x16_bf16(kf1[d0], qf[d0], s1, 0, 0, 0);
; #pragma unroll
;         for (int r = 4 * d0; r < 4 * d0 + 4; ++r) { if (MASKED) { const int t = (r & 3) + 8 * (r >> 2) + dq; if (t < a0 || t > b0) s0[r] = NEG; } s0[r] = __builtin_amdgcn_exp2f(s0[r]); }
;         T64_SB();
;     }
;     u32x4 w00, w01;
;     w00.x = cvtpk(s0[0], s0[1]); w00.y = cvtpk(s0[2], s0[3]); w00.z = cvtpk(s0[4], s0[5]); w00.w = cvtpk(s0[6], s0[7]);
;     w01.x = cvtpk(s0[8], s0[9]); w01.y = cvtpk(s0[10], s0[11]); w01.z = cvtpk(s0[12], s0[13]); w01.w = cvtpk(s0[14], s0[15]);
;     const bf16x8 p00 = __builtin_bit_cast(bf16x8, w00), p01 = __builtin_bit_cast(bf16x8, w01);
;     l += (((s0[0] + s0[1]) + (s0[2] + s0[3])) + ((s0[4] + s0[5]) + (s0[6] + s0[7]))) + (((s0[8] + s0[9]) + (s0[10] + s0[11])) + ((s0[12] + s0[13]) + (s0[14] + s0[15])));
;     ...
;     T64_SB();
;     o0 = __builtin_amdgcn_mfma_f32_32x32x16_bf16(T64_VF(0, 0), p00, o0, 0, 0, 0); T64_EXP1(0);  T64_SB();
;     o1 = __builtin_amdgcn_mfma_f32_32x32x16_bf16(T64_VF(1, 0), p00, o1, 0, 0, 0); T64_EXP1(4);  T64_SB();
;     o0 = __builtin_amdgcn_mfma_f32_32x32x16_bf16(T64_VF(0, 1), p01, o0, 0, 0, 0); T64_EXP1(8);  T64_SB();
.Lam_v4:
	ds_read_b128 v[10:13], v0
	ds_read_b128 v[64:67], v0 offset:32
	ds_read_b128 v[108:111], v0 offset:4608
	ds_read_b128 v[112:115], v0 offset:4640
	ds_read_b128 v[68:71], v0 offset:64
	ds_read_b128 v[72:75], v0 offset:96
	ds_read_b128 v[116:119], v0 offset:4672
	ds_read_b128 v[120:123], v0 offset:4704
	s_waitcnt lgkmcnt(7)
	s_waitcnt vmcnt(2)
	v_mfma_f32_32x32x16_bf16 v[76:91], v[10:13], v[92:95], v[16:31]
	ds_read_b64_tr_b16 v[10:11], v244 offset:9216
	ds_read_b64_tr_b16 v[12:13], v244 offset:9728
	ds_read_b64_tr_b16 v[124:125], v244 offset:10240
	ds_read_b64_tr_b16 v[126:127], v244 offset:10752
	ds_read_b64_tr_b16 v[132:133], v244 offset:11264
	ds_read_b64_tr_b16 v[134:135], v244 offset:11776
	ds_read_b64_tr_b16 v[136:137], v244 offset:12288
	ds_read_b64_tr_b16 v[138:139], v244 offset:12800
	ds_read_b64_tr_b16 v[140:141], v244 offset:13376
	ds_read_b64_tr_b16 v[142:143], v244 offset:13888
	ds_read_b64_tr_b16 v[144:145], v244 offset:14400
	ds_read_b64_tr_b16 v[146:147], v244 offset:14912
	ds_read_b64_tr_b16 v[152:153], v244 offset:15424
	ds_read_b64_tr_b16 v[154:155], v244 offset:15936
	ds_read_b64_tr_b16 v[156:157], v244 offset:16448
	ds_read_b64_tr_b16 v[158:159], v244 offset:16960
	s_waitcnt lgkmcnt(14)
	v_mfma_f32_32x32x16_bf16 v[76:91], v[64:67], v[96:99], v[76:91]
	v_mfma_f32_32x32x16_bf16 v[76:91], v[68:71], v[100:103], v[76:91]
	v_mfma_f32_32x32x16_bf16 v[76:91], v[72:75], v[104:107], v[76:91]
	s_nop 11
	v_exp_f32_e32 v14, v76
	v_exp_f32_e32 v148, v77
	v_exp_f32_e32 v160, v78
	v_exp_f32_e32 v162, v79
	s_waitcnt vmcnt(2)
	v_mfma_f32_32x32x16_bf16 v[64:79], v[108:111], v[92:95], v[200:215]
	v_exp_f32_e32 v108, v80
	v_exp_f32_e32 v110, v81
	v_exp_f32_e32 v164, v82
	v_exp_f32_e32 v166, v83
	v_mfma_f32_32x32x16_bf16 v[64:79], v[112:115], v[96:99], v[64:79]
	v_exp_f32_e32 v112, v84
	v_exp_f32_e32 v114, v85
	v_exp_f32_e32 v168, v86
	v_exp_f32_e32 v170, v87
	v_mfma_f32_32x32x16_bf16 v[64:79], v[116:119], v[100:103], v[64:79]
	v_exp_f32_e32 v88, v88
	v_exp_f32_e32 v116, v89
	v_exp_f32_e32 v90, v90
	v_exp_f32_e32 v118, v91
	v_mfma_f32_32x32x16_bf16 v[64:79], v[120:123], v[104:107], v[64:79]
	v_cvt_pk_bf16_f32 v80, v14, v148
	v_cvt_pk_bf16_f32 v81, v160, v162
	v_cvt_pk_bf16_f32 v82, v108, v110
	v_cvt_pk_bf16_f32 v83, v164, v166
	v_cvt_pk_bf16_f32 v84, v112, v114
	v_cvt_pk_bf16_f32 v85, v168, v170
	v_cvt_pk_bf16_f32 v86, v88, v116
	v_cvt_pk_bf16_f32 v87, v90, v118
	s_nop 1
	v_mfma_f32_32x32x16_bf16 v[32:47], v[10:13], v[80:83], v[32:47]
	s_nop 2
	v_exp_f32_e32 v15, v64
	v_exp_f32_e32 v149, v65
	v_exp_f32_e32 v161, v66
	v_exp_f32_e32 v163, v67
	s_waitcnt lgkmcnt(6)
	v_mfma_f32_32x32x16_bf16 v[48:63], v[140:143], v[80:83], v[48:63]
	v_exp_f32_e32 v109, v68
	v_exp_f32_e32 v111, v69
	v_exp_f32_e32 v165, v70
	v_exp_f32_e32 v167, v71
	v_mfma_f32_32x32x16_bf16 v[32:47], v[124:127], v[84:87], v[32:47]
	v_exp_f32_e32 v113, v72
	v_exp_f32_e32 v115, v73
	v_exp_f32_e32 v169, v74
	v_exp_f32_e32 v171, v75
	s_waitcnt lgkmcnt(4)
	v_mfma_f32_32x32x16_bf16 v[48:63], v[144:147], v[84:87], v[48:63]
	v_exp_f32_e32 v89, v76
	v_exp_f32_e32 v117, v77
	v_exp_f32_e32 v91, v78
	v_exp_f32_e32 v119, v79
	v_cvt_pk_bf16_f32 v10, v15, v149
	v_cvt_pk_bf16_f32 v11, v161, v163
	v_cvt_pk_bf16_f32 v12, v109, v111
	v_cvt_pk_bf16_f32 v13, v165, v167
	v_pk_add_f32 v[14:15], v[14:15], v[148:149]
	v_pk_add_f32 v[160:161], v[160:161], v[162:163]
	v_mfma_f32_32x32x16_bf16 v[32:47], v[132:135], v[10:13], v[32:47]
	v_cvt_pk_bf16_f32 v64, v113, v115
	v_cvt_pk_bf16_f32 v65, v169, v171
	v_cvt_pk_bf16_f32 v66, v89, v117
	v_cvt_pk_bf16_f32 v67, v91, v119
	v_pk_add_f32 v[108:109], v[108:109], v[110:111]
	v_pk_add_f32 v[164:165], v[164:165], v[166:167]
	s_waitcnt lgkmcnt(2)
	v_mfma_f32_32x32x16_bf16 v[48:63], v[152:155], v[10:13], v[48:63]
	v_pk_add_f32 v[112:113], v[112:113], v[114:115]
	v_pk_add_f32 v[168:169], v[168:169], v[170:171]
	v_pk_add_f32 v[88:89], v[88:89], v[116:117]
	v_pk_add_f32 v[90:91], v[90:91], v[118:119]
	v_pk_add_f32 v[14:15], v[14:15], v[160:161]
	v_pk_add_f32 v[108:109], v[108:109], v[164:165]
	v_mfma_f32_32x32x16_bf16 v[32:47], v[136:139], v[64:67], v[32:47]
	v_pk_add_f32 v[112:113], v[112:113], v[168:169]
	v_pk_add_f32 v[88:89], v[88:89], v[90:91]
	v_pk_add_f32 v[14:15], v[14:15], v[108:109]
	v_pk_add_f32 v[112:113], v[112:113], v[88:89]
	s_waitcnt lgkmcnt(0)
	v_mfma_f32_32x32x16_bf16 v[48:63], v[156:159], v[64:67], v[48:63]
	v_pk_add_f32 v[14:15], v[14:15], v[112:113]
	s_nop 0
	v_add_f32_e32 v0, v150, v14
	v_add_f32_e32 v150, v0, v15
	s_branch .Lam_tail
.Lam_v3:
	ds_read_b128 v[10:13], v0
	ds_read_b128 v[64:67], v0 offset:32
	ds_read_b128 v[68:71], v0 offset:64
	ds_read_b128 v[72:75], v0 offset:96
	s_waitcnt lgkmcnt(3)
	s_waitcnt vmcnt(2)
	v_mfma_f32_32x32x16_bf16 v[76:91], v[10:13], v[92:95], v[200:215]
	ds_read_b64_tr_b16 v[10:11], v244 offset:9216
	ds_read_b64_tr_b16 v[12:13], v244 offset:9728
	ds_read_b64_tr_b16 v[124:125], v244 offset:10240
	ds_read_b64_tr_b16 v[126:127], v244 offset:10752
	ds_read_b64_tr_b16 v[140:141], v244 offset:13376
	ds_read_b64_tr_b16 v[142:143], v244 offset:13888
	ds_read_b64_tr_b16 v[144:145], v244 offset:14400
	ds_read_b64_tr_b16 v[146:147], v244 offset:14912
	s_waitcnt lgkmcnt(8)
	v_mfma_f32_32x32x16_bf16 v[76:91], v[64:67], v[96:99], v[76:91]
	v_mfma_f32_32x32x16_bf16 v[76:91], v[68:71], v[100:103], v[76:91]
	v_mfma_f32_32x32x16_bf16 v[76:91], v[72:75], v[104:107], v[76:91]
	s_nop 11
	v_exp_f32_e32 v14, v76
	v_exp_f32_e32 v148, v77
	v_exp_f32_e32 v160, v78
	v_exp_f32_e32 v162, v79
	v_exp_f32_e32 v108, v80
	v_exp_f32_e32 v110, v81
	v_exp_f32_e32 v164, v82
	v_exp_f32_e32 v166, v83
	v_exp_f32_e32 v112, v84
	v_exp_f32_e32 v114, v85
	v_exp_f32_e32 v168, v86
	v_exp_f32_e32 v170, v87
	v_exp_f32_e32 v88, v88
	v_exp_f32_e32 v116, v89
	v_exp_f32_e32 v90, v90
	v_exp_f32_e32 v118, v91
	v_cvt_pk_bf16_f32 v80, v14, v148
	v_cvt_pk_bf16_f32 v81, v160, v162
	v_cvt_pk_bf16_f32 v82, v108, v110
	v_cvt_pk_bf16_f32 v83, v164, v166
	v_cvt_pk_bf16_f32 v84, v112, v114
	v_cvt_pk_bf16_f32 v85, v168, v170
	v_cvt_pk_bf16_f32 v86, v88, v116
	v_cvt_pk_bf16_f32 v87, v90, v118
	s_nop 1
	s_waitcnt lgkmcnt(0)
	v_mfma_f32_32x32x16_bf16 v[32:47], v[10:13], v[80:83], v[32:47]
	v_mfma_f32_32x32x16_bf16 v[48:63], v[140:143], v[80:83], v[48:63]
	v_mfma_f32_32x32x16_bf16 v[32:47], v[124:127], v[84:87], v[32:47]
	v_mfma_f32_32x32x16_bf16 v[48:63], v[144:147], v[84:87], v[48:63]
	v_add_f32_e32 v14, v14, v148
	v_add_f32_e32 v160, v160, v162
	v_add_f32_e32 v108, v108, v110
	v_add_f32_e32 v164, v164, v166
	v_add_f32_e32 v112, v112, v114
	v_add_f32_e32 v168, v168, v170
	v_add_f32_e32 v88, v88, v116
	v_add_f32_e32 v90, v90, v118
	v_add_f32_e32 v14, v14, v160
	v_add_f32_e32 v108, v108, v164
	v_add_f32_e32 v112, v112, v168
	v_add_f32_e32 v88, v88, v90
	v_add_f32_e32 v14, v14, v108
	v_add_f32_e32 v112, v112, v88
	v_add_f32_e32 v14, v14, v112
	v_add_f32_e32 v150, v150, v14

; template <int MODE, bool FIX> ...
;     ...
;         int i = 0;
;         for (; i < nmask; ++i) {
;             ATT_STEP_PRE(i)
;             if (MODE == 0) {
;                 const int tl = ATT_SEQ_TL(i); const int dA = 2 * tl - s_sub, dB = dA + 1;
;                 const int a0 = (dA < 0 || dA > 8) ? 99 : (dA == 0 ? 0 : -99), b0 = (dA < 0 || dA > 8) ? -99 : (dA == 8 ? 0 : 99);
;                 const int a1 = (dB < 0 || dB > 8) ? 99 : (dB == 0 ? 0 : -99), b1 = (dB < 0 || dB > 8) ? -99 : (dB == 8 ? 0 : 99);
;                 tile64<true>(buf, qf, o0, o1, l, lane, r32, hi, cinit, a0, b0, a1, b1);
;             } else {
;                 const int kr = kr_lo + i;
;                 const unsigned vm = (kr >= wa_lo && kr <= wa_hi && (unsigned)(kr - rs) < 8u) ? colmask : 0u;
;                 const int bidx0 = (kr - qrow + 7) * 31 + kc0 + 4 * hi - qc + 15;
;                 half_step<3, true>(buf, kc0, qf, o0, o1, m, l, lane, r32, hi, rpbl, bidx0, vm, cinit);
;             }
;         }
;         for (; i < NT; ++i) {
;             ATT_STEP_PRE(i)
;             tile64<false>(buf, qf, o0, o1, l, lane, r32, hi, cinit, 0, 0, 0, 0);
;         }
.LBB0_660:
	s_and_b64 vcc, exec, s[70:71]
	s_cbranch_vccz .LBB0_662
	v_mov_b32_e32 v14, v1
	v_mov_b32_e32 v15, v1
	v_mov_b32_e32 v0, v1
	s_waitcnt vmcnt(4)
	v_mov_b32_e32 v2, v1
	v_mov_b32_e32 v3, v1
	v_mov_b32_e32 v4, v1
	v_mov_b32_e32 v5, v1
	v_mov_b32_e32 v6, v1
	v_mov_b32_e32 v7, v1
	v_mov_b32_e32 v8, v1
	v_mov_b32_e32 v9, v1
	v_mov_b32_e32 v10, v1
	v_mov_b32_e32 v11, v1
	v_mov_b32_e32 v12, v1
	v_mov_b32_e32 v13, v1
	v_mov_b64_e32 v[62:63], v[14:15]
	v_mov_b64_e32 v[46:47], v[14:15]
	v_mov_b64_e32 v[60:61], v[12:13]
	v_mov_b64_e32 v[58:59], v[10:11]
	v_mov_b64_e32 v[56:57], v[8:9]
	v_mov_b64_e32 v[54:55], v[6:7]
	v_mov_b64_e32 v[52:53], v[4:5]
	v_mov_b64_e32 v[50:51], v[2:3]
	v_mov_b64_e32 v[48:49], v[0:1]
	v_mov_b64_e32 v[44:45], v[12:13]
	v_mov_b64_e32 v[42:43], v[10:11]
	v_mov_b64_e32 v[40:41], v[8:9]
	v_mov_b64_e32 v[38:39], v[6:7]
	v_mov_b64_e32 v[36:37], v[4:5]
	v_mov_b64_e32 v[34:35], v[2:3]
	v_mov_b64_e32 v[32:33], v[0:1]
	v_mov_b64_e32 v[6:7], v[112:113]
	v_mov_b64_e32 v[2:3], v[108:109]
	v_mov_b32_e32 v150, 0
	s_mov_b32 s52, s72
	v_mov_b64_e32 v[8:9], v[114:115]
	v_mov_b64_e32 v[4:5], v[110:111]

; template <bool MASKED>
; __device__ __forceinline__ void tile64(const LAS unsigned char* buf, const bf16x8 (&qf)[4], f32x16& o0, f32x16& o1, float& l, int lane, int r32, int hi, const f32x16& cinit,
;                                        int a0, int b0, int a1, int b1) {
;     ...
;     const LAS unsigned char* kp = buf + r32 * KSTR + hi * 16;
;     const LAS unsigned char* vp = buf + K_BYTES + (4 * hi + ((lane & 15) >> 2)) * 64 + 32 * ((lane >> 4) & 1) + 8 * (lane & 3);
;     const int dq = 4 * hi - r32; const float NEG = -INFINITY;
;     bf16x8 kf0[4], kf1[4];
; #pragma unroll
;     for (int d0 = 0; d0 < 4; ++d0) { kf0[d0] = *(const LAS bf16x8*)(kp + d0 * 32); kf1[d0] = *(const LAS bf16x8*)(kp + 32 * KSTR + d0 * 32); }
;     T64_SB();
;     f32x16 s0 = cinit, s1 = cinit;
; #pragma unroll
;     for (int d0 = 0; d0 < 4; ++d0) s0 = __builtin_amdgcn_mfma_f32_32x32x16_bf16(kf0[d0], qf[d0], s0, 0, 0, 0);
;     s16x4 va[2][8];
; #pragma unroll
;     for (int dh = 0; dh < 2; ++dh)
; #pragma unroll
;         for (int j = 0; j < 8; ++j) va[dh][j] = vtr(vp + dh * V_HALF + j * 512);
;     T64_SB();
; template <int MODE, bool FIX> ...
;     ...
;         u32x4 kA, vA;
;         { const size_t ro_ = (size_t)ATT_SEQ_ROW(0) * INC; kA = *(const u32x4*)(gk + ro_); vA = *(const u32x4*)(gv + ro_); }
;         int i = 0;
;         for (; i < nmask; ++i) {
;             ATT_STEP_PRE(i)
;             if (MODE == 0) {
;                 const int tl = ATT_SEQ_TL(i); const int dA = 2 * tl - s_sub, dB = dA + 1;
;                 const int a0 = (dA < 0 || dA > 8) ? 99 : (dA == 0 ? 0 : -99), b0 = (dA < 0 || dA > 8) ? -99 : (dA == 8 ? 0 : 99);
;                 const int a1 = (dB < 0 || dB > 8) ? 99 : (dB == 0 ? 0 : -99), b1 = (dB < 0 || dB > 8) ? -99 : (dB == 8 ? 0 : 99);
;                 tile64<true>(buf, qf, o0, o1, l, lane, r32, hi, cinit, a0, b0, a1, b1);
;             } else {
;                 const int kr = kr_lo + i;
;                 const unsigned vm = (kr >= wa_lo && kr <= wa_hi && (unsigned)(kr - rs) < 8u) ? colmask : 0u;
;                 const int bidx0 = (kr - qrow + 7) * 31 + kc0 + 4 * hi - qc + 15;
;                 half_step<3, true>(buf, kc0, qf, o0, o1, m, l, lane, r32, hi, rpbl, bidx0, vm, cinit);
;             }
;         }
;         for (; i < NT; ++i) {
;             ATT_STEP_PRE(i)
;             tile64<false>(buf, qf, o0, o1, l, lane, r32, hi, cinit, 0, 0, 0, 0);
.LBB0_663:
	v_mad_i64_i32 v[6:7], s[78:79], s79, v221, v[130:131]
	global_load_dwordx4 v[2:5], v[6:7], off offset:1024
	s_nop 0
	global_load_dwordx4 v[6:9], v[6:7], off offset:1280
	v_add3_u32 v0, s77, v179, v189
	ds_read_b128 v[10:13], v0
	ds_read_b128 v[64:67], v0 offset:32
	ds_read_b128 v[108:111], v0 offset:4608
	ds_read_b128 v[112:115], v0 offset:4640
	ds_read_b128 v[68:71], v0 offset:64
	ds_read_b128 v[72:75], v0 offset:96
	ds_read_b128 v[116:119], v0 offset:4672
	ds_read_b128 v[120:123], v0 offset:4704
	v_add3_u32 v0, s77, v190, v193
	s_waitcnt lgkmcnt(7)
	s_waitcnt vmcnt(2)
	v_mfma_f32_32x32x16_bf16 v[76:91], v[10:13], v[92:95], v[16:31]
	v_add3_u32 v0, v0, v191, v192
	ds_read_b64_tr_b16 v[10:11], v0 offset:9216
	ds_read_b64_tr_b16 v[12:13], v0 offset:9728
	ds_read_b64_tr_b16 v[124:125], v0 offset:10240
	ds_read_b64_tr_b16 v[126:127], v0 offset:10752
	ds_read_b64_tr_b16 v[132:133], v0 offset:11264
	ds_read_b64_tr_b16 v[134:135], v0 offset:11776
	ds_read_b64_tr_b16 v[136:137], v0 offset:12288
	ds_read_b64_tr_b16 v[138:139], v0 offset:12800
	ds_read_b64_tr_b16 v[140:141], v0 offset:13376
	ds_read_b64_tr_b16 v[142:143], v0 offset:13888
	ds_read_b64_tr_b16 v[144:145], v0 offset:14400
	ds_read_b64_tr_b16 v[146:147], v0 offset:14912
	ds_read_b64_tr_b16 v[152:153], v0 offset:15424
	ds_read_b64_tr_b16 v[154:155], v0 offset:15936
	ds_read_b64_tr_b16 v[156:157], v0 offset:16448
	ds_read_b64_tr_b16 v[158:159], v0 offset:16960
	s_waitcnt lgkmcnt(14)
	v_mfma_f32_32x32x16_bf16 v[76:91], v[64:67], v[96:99], v[76:91]
	v_mfma_f32_32x32x16_bf16 v[76:91], v[68:71], v[100:103], v[76:91]
	v_mfma_f32_32x32x16_bf16 v[76:91], v[72:75], v[104:107], v[76:91]
	s_nop 11
	v_exp_f32_e32 v14, v76
	v_exp_f32_e32 v148, v77
	v_exp_f32_e32 v160, v78
	v_exp_f32_e32 v162, v79
	s_waitcnt vmcnt(2)
	v_mfma_f32_32x32x16_bf16 v[64:79], v[108:111], v[92:95], v[16:31]
	v_exp_f32_e32 v108, v80
	v_exp_f32_e32 v110, v81
	v_exp_f32_e32 v164, v82
	v_exp_f32_e32 v166, v83
	v_mfma_f32_32x32x16_bf16 v[64:79], v[112:115], v[96:99], v[64:79]
	v_exp_f32_e32 v112, v84
	v_exp_f32_e32 v114, v85
	v_exp_f32_e32 v168, v86
	v_exp_f32_e32 v170, v87
	v_mfma_f32_32x32x16_bf16 v[64:79], v[116:119], v[100:103], v[64:79]
	v_exp_f32_e32 v88, v88
	v_exp_f32_e32 v116, v89
	v_exp_f32_e32 v90, v90
	v_exp_f32_e32 v118, v91
	v_mfma_f32_32x32x16_bf16 v[64:79], v[120:123], v[104:107], v[64:79]
	v_cvt_pk_bf16_f32 v80, v14, v148
	v_cvt_pk_bf16_f32 v81, v160, v162
	v_cvt_pk_bf16_f32 v82, v108, v110
	v_cvt_pk_bf16_f32 v83, v164, v166
	v_cvt_pk_bf16_f32 v84, v112, v114
	v_cvt_pk_bf16_f32 v85, v168, v170
	v_cvt_pk_bf16_f32 v86, v88, v116
	v_cvt_pk_bf16_f32 v87, v90, v118
	v_mfma_f32_32x32x16_bf16 v[32:47], v[10:13], v[80:83], v[32:47]
	s_nop 2
	v_exp_f32_e32 v15, v64
	v_exp_f32_e32 v149, v65
	v_exp_f32_e32 v161, v66
	v_exp_f32_e32 v163, v67
	s_waitcnt lgkmcnt(6)
	v_mfma_f32_32x32x16_bf16 v[48:63], v[140:143], v[80:83], v[48:63]
	v_exp_f32_e32 v109, v68
	v_exp_f32_e32 v111, v69
	v_exp_f32_e32 v165, v70
	v_exp_f32_e32 v167, v71
	v_mfma_f32_32x32x16_bf16 v[32:47], v[124:127], v[84:87], v[32:47]
	v_exp_f32_e32 v113, v72
	v_exp_f32_e32 v115, v73
	v_exp_f32_e32 v169, v74
	v_exp_f32_e32 v171, v75
	s_waitcnt lgkmcnt(4)
	v_mfma_f32_32x32x16_bf16 v[48:63], v[144:147], v[84:87], v[48:63]
	v_exp_f32_e32 v89, v76
	v_exp_f32_e32 v117, v77
	v_exp_f32_e32 v91, v78
	v_exp_f32_e32 v119, v79
	v_cvt_pk_bf16_f32 v10, v15, v149
	v_cvt_pk_bf16_f32 v11, v161, v163
	v_cvt_pk_bf16_f32 v12, v109, v111
	v_cvt_pk_bf16_f32 v13, v165, v167
	v_pk_add_f32 v[14:15], v[14:15], v[148:149]
	v_pk_add_f32 v[68:69], v[160:161], v[162:163]
	v_mfma_f32_32x32x16_bf16 v[32:47], v[132:135], v[10:13], v[32:47]
	v_cvt_pk_bf16_f32 v64, v113, v115
	v_cvt_pk_bf16_f32 v65, v169, v171
	v_cvt_pk_bf16_f32 v66, v89, v117
	v_cvt_pk_bf16_f32 v67, v91, v119
	v_add_f32_e64 v14, v14, v68
	v_add_f32_e64 v15, v15, v69
	v_pk_add_f32 v[68:69], v[108:109], v[110:111]
	v_pk_add_f32 v[70:71], v[164:165], v[166:167]
	s_waitcnt lgkmcnt(2)
	v_mfma_f32_32x32x16_bf16 v[48:63], v[152:155], v[10:13], v[48:63]
	v_add_f32_e64 v68, v68, v70
	v_add_f32_e64 v69, v69, v71
	v_add_f32_e64 v12, v112, v114
	v_add_f32_e64 v13, v113, v115
	v_add_f32_e64 v10, v14, v68
	v_add_f32_e64 v11, v15, v69
	v_pk_add_f32 v[14:15], v[168:169], v[170:171]
	v_pk_add_f32 v[68:69], v[90:91], v[118:119]
	v_pk_add_f32 v[12:13], v[12:13], v[14:15]
	v_pk_add_f32 v[14:15], v[88:89], v[116:117]
	v_mfma_f32_32x32x16_bf16 v[32:47], v[136:139], v[64:67], v[32:47]
	v_add_f32_e64 v14, v14, v68
	v_add_f32_e64 v15, v15, v69
	s_andn2_b64 vcc, exec, s[70:71]
	v_add_f32_e64 v12, v12, v14
	v_add_f32_e64 v13, v13, v15
	v_pk_add_f32 v[10:11], v[10:11], v[12:13]
	s_nop 0
	v_add_f32_e32 v0, v150, v10
	s_waitcnt lgkmcnt(0)
	v_mfma_f32_32x32x16_bf16 v[48:63], v[156:159], v[64:67], v[48:63]
	v_add_f32_e32 v150, v0, v11
	s_cbranch_vccz .LBB0_672
.LBB0_664:
	s_bitcmp1_b32 s75, 0
	s_cselect_b32 s70, 0x4480, 0
	s_add_i32 s77, s70, 0
	v_add_u32_e32 v0, s77, v178
	s_mov_b32 s78, s75
	s_cmp_lg_u32 s36, 0
	s_cbranch_scc1 .La_nw2
	s_waitcnt vmcnt(0)
.La_nw2:
	s_mov_b32 s36, 0
	ds_write_b128 v0, v[2:5]
	v_add_u32_e32 v0, s77, v194
	s_add_i32 s75, s75, 1
	ds_write_b128 v0, v[6:9] offset:9216
	s_cmp_ge_u32 s75, s53
	s_waitcnt lgkmcnt(0)
	s_barrier
	s_cselect_b64 s[70:71], -1, 0
	s_cmp_lt_u32 s75, s53
	s_cselect_b32 s78, s75, s78
	s_cmp_ge_u32 s78, s2
	s_mov_b64 s[90:91], -1
	s_cbranch_scc0 .LBB0_670
	s_sub_i32 s80, s78, s2
	s_cmp_gt_u32 s80, s3
	s_cbranch_scc1 .LBB0_667
	s_add_i32 s79, s52, s78
	s_lshl_b32 s79, s79, 6
	s_add_i32 s79, s79, s0
	s_mov_b64 s[90:91], 0
